# combo12 + hidconv thin phase: four source blocks (8 loads) requested per trip before converting, 11 trips instead of 44 drained trips
# speedup vs baseline: 1.0137x; 1.0007x over previous
; #define GAS __attribute__((address_space(1)))
; __device__ __forceinline__ float bf_lo(unsigned w) { return __uint_as_float(w << 16); }
; __device__ __forceinline__ float bf_hi(unsigned w) { return __uint_as_float(w & 0xffff0000u); }
; __device__ __forceinline__ void phase_hidconv(LAS unsigned char* lds, const bf16_t* HIDb, unsigned char* HID8, const float* hmx, float* hrs, int grp, int rank, int wv) {
;     ...
;     for (int ui = wave; ui < 2 * 11 * 16; ui += 8) {
;         const int st8 = ui & 15, kk = (ui >> 4) % 11, h = (ui >> 4) / 11;
;         const int kt8 = mem * 11 + kk, rb = st8 >> 1, h2 = st8 & 1;
;         const GAS char* src = (const GAS char*)HIDb + ((size_t)(2 * pm + h) * KT_F + (2 * kt8 + h2)) * pg8::HTB + (size_t)(rb * 2048) + lane * 16;
;         GAS char* dst = (GAS char*)HID8 + ((size_t)(2 * pm + h) * KT_F8 + kt8) * pg8::HTB + (size_t)(st8 * 1024);
;         const u32x4 a = *(const GAS u32x4*)src, b = *(const GAS u32x4*)(src + 1024);
;         const float s_ = sc[h * 128 + rb * 16 + rr];
;         u32x2 wa, wb;
;         wa.x = cvt_i8x4(bf_lo(a.x) * s_, bf_hi(a.x) * s_, bf_lo(a.y) * s_, bf_hi(a.y) * s_); wa.y = cvt_i8x4(bf_lo(a.z) * s_, bf_hi(a.z) * s_, bf_lo(a.w) * s_, bf_hi(a.w) * s_);
;         wb.x = cvt_i8x4(bf_lo(b.x) * s_, bf_hi(b.x) * s_, bf_lo(b.y) * s_, bf_hi(b.y) * s_); wb.y = cvt_i8x4(bf_lo(b.z) * s_, bf_hi(b.z) * s_, bf_lo(b.w) * s_, bf_hi(b.w) * s_);
;         *(GAS u32x2*)(dst + d0) = wa; *(GAS u32x2*)(dst + d1) = wb;
.LBB0_573:
	s_ashr_i32 s4, s0, 4
	s_mul_hi_i32 s5, s4, 0x2e8ba2e9
	s_lshr_b32 s7, s5, 31
	s_ashr_i32 s5, s5, 1
	s_add_i32 s7, s5, s7
	s_mul_i32 s5, s7, 11
	s_sub_i32 s4, s4, s5
	s_mul_i32 s5, s66, 11
	s_add_i32 s8, s4, s5
	s_lshl_b32 s11, s8, 1
	s_add_i32 s10, s7, s13
	s_or_b32 s11, s11, s3
	s_and_b32 s6, s0, 15
	s_bfe_u32 s9, s0, 0x30001
	s_mul_i32 s4, s10, 0x58
	s_ashr_i32 s12, s11, 31
	s_mul_hi_i32 s5, s10, 0x58
	s_add_u32 s4, s4, s11
	s_addc_u32 s5, s5, s12
	s_lshl_b64 s[4:5], s[4:5], 14
	s_add_u32 s4, s64, s4
	s_addc_u32 s5, s65, s5
	s_lshl_b32 s11, s9, 11
	s_add_u32 s4, s4, s11
	s_addc_u32 s5, s5, 0
	v_lshl_add_u64 v[12:13], s[4:5], 0, v[0:1]
	global_load_dwordx4 v[64:67], v[12:13], off
	s_nop 0
	global_load_dwordx4 v[68:71], v[12:13], off offset:1024
	s_add_i32 s0, s0, 8
	s_ashr_i32 s4, s0, 4
	s_mul_hi_i32 s5, s4, 0x2e8ba2e9
	s_lshr_b32 s7, s5, 31
	s_ashr_i32 s5, s5, 1
	s_add_i32 s7, s5, s7
	s_mul_i32 s5, s7, 11
	s_sub_i32 s4, s4, s5
	s_mul_i32 s5, s66, 11
	s_add_i32 s8, s4, s5
	s_lshl_b32 s11, s8, 1
	s_add_i32 s10, s7, s13
	s_or_b32 s11, s11, s3
	s_and_b32 s6, s0, 15
	s_bfe_u32 s9, s0, 0x30001
	s_mul_i32 s4, s10, 0x58
	s_ashr_i32 s12, s11, 31
	s_mul_hi_i32 s5, s10, 0x58
	s_add_u32 s4, s4, s11
	s_addc_u32 s5, s5, s12
	s_lshl_b64 s[4:5], s[4:5], 14
	s_add_u32 s4, s64, s4
	s_addc_u32 s5, s65, s5
	s_lshl_b32 s11, s9, 11
	s_add_u32 s4, s4, s11
	s_addc_u32 s5, s5, 0
	v_lshl_add_u64 v[12:13], s[4:5], 0, v[0:1]
	global_load_dwordx4 v[72:75], v[12:13], off
	s_nop 0
	global_load_dwordx4 v[76:79], v[12:13], off offset:1024
	s_add_i32 s0, s0, 8
	s_ashr_i32 s4, s0, 4
	s_mul_hi_i32 s5, s4, 0x2e8ba2e9
	s_lshr_b32 s7, s5, 31
	s_ashr_i32 s5, s5, 1
	s_add_i32 s7, s5, s7
	s_mul_i32 s5, s7, 11
	s_sub_i32 s4, s4, s5
	s_mul_i32 s5, s66, 11
	s_add_i32 s8, s4, s5
	s_lshl_b32 s11, s8, 1
	s_add_i32 s10, s7, s13
	s_or_b32 s11, s11, s3
	s_and_b32 s6, s0, 15
	s_bfe_u32 s9, s0, 0x30001
	s_mul_i32 s4, s10, 0x58
	s_ashr_i32 s12, s11, 31
	s_mul_hi_i32 s5, s10, 0x58
	s_add_u32 s4, s4, s11
	s_addc_u32 s5, s5, s12
	s_lshl_b64 s[4:5], s[4:5], 14
	s_add_u32 s4, s64, s4
	s_addc_u32 s5, s65, s5
	s_lshl_b32 s11, s9, 11
	s_add_u32 s4, s4, s11
	s_addc_u32 s5, s5, 0
	v_lshl_add_u64 v[12:13], s[4:5], 0, v[0:1]
	global_load_dwordx4 v[80:83], v[12:13], off
	s_nop 0
	global_load_dwordx4 v[84:87], v[12:13], off offset:1024
	s_add_i32 s0, s0, 8
	s_ashr_i32 s4, s0, 4
	s_mul_hi_i32 s5, s4, 0x2e8ba2e9
	s_lshr_b32 s7, s5, 31
	s_ashr_i32 s5, s5, 1
	s_add_i32 s7, s5, s7
	s_mul_i32 s5, s7, 11
	s_sub_i32 s4, s4, s5
	s_mul_i32 s5, s66, 11
	s_add_i32 s8, s4, s5
	s_lshl_b32 s11, s8, 1
	s_add_i32 s10, s7, s13
	s_or_b32 s11, s11, s3
	s_and_b32 s6, s0, 15
	s_bfe_u32 s9, s0, 0x30001
	s_mul_i32 s4, s10, 0x58
	s_ashr_i32 s12, s11, 31
	s_mul_hi_i32 s5, s10, 0x58
	s_add_u32 s4, s4, s11
	s_addc_u32 s5, s5, s12
	s_lshl_b64 s[4:5], s[4:5], 14
	s_add_u32 s4, s64, s4
	s_addc_u32 s5, s65, s5
	s_lshl_b32 s11, s9, 11
	s_add_u32 s4, s4, s11
	s_addc_u32 s5, s5, 0
	v_lshl_add_u64 v[12:13], s[4:5], 0, v[0:1]
	global_load_dwordx4 v[88:91], v[12:13], off
	s_nop 0
	global_load_dwordx4 v[92:95], v[12:13], off offset:1024
	s_sub_i32 s0, s0, 24
	s_ashr_i32 s4, s0, 4
	s_mul_hi_i32 s5, s4, 0x2e8ba2e9
	s_lshr_b32 s7, s5, 31
	s_ashr_i32 s5, s5, 1
	s_add_i32 s7, s5, s7
	s_mul_i32 s5, s7, 11
	s_sub_i32 s4, s4, s5
	s_mul_i32 s5, s66, 11
	s_add_i32 s8, s4, s5
	s_lshl_b32 s11, s8, 1
	s_add_i32 s10, s7, s13
	s_or_b32 s11, s11, s3
	s_and_b32 s6, s0, 15
	s_bfe_u32 s9, s0, 0x30001
	s_waitcnt vmcnt(6)
	v_mov_b32_e32 v8, v64
	v_mov_b32_e32 v9, v65
	v_mov_b32_e32 v10, v66
	v_mov_b32_e32 v11, v67
	v_mov_b32_e32 v12, v68
	v_mov_b32_e32 v13, v69
	v_mov_b32_e32 v14, v70
	v_mov_b32_e32 v15, v71
	s_mul_hi_i32 s5, s10, 44
	s_mul_i32 s10, s10, 44
	s_ashr_i32 s11, s8, 31
	s_add_u32 s4, s10, s8
	s_addc_u32 s5, s5, s11
	s_lshl_b64 s[4:5], s[4:5], 14
	s_add_u32 s4, s1, s4
	s_addc_u32 s5, s2, s5
	s_lshl_b32 s6, s6, 10
	s_add_u32 s4, s4, s6
	s_addc_u32 s5, s5, 0
	s_lshl_b32 s6, s7, 9
	s_add_i32 s6, s40, s6
	s_lshl_b32 s7, s9, 6
	s_add_i32 s6, s6, s7
	v_lshl_add_u32 v7, v6, 2, s6
	ds_read_b32 v7, v7
	v_lshlrev_b32_e32 v16, 16, v8
	v_and_b32_e32 v8, 0xffff0000, v8
	s_waitcnt lgkmcnt(0)
	v_fmaak_f32 v16, v7, v16, 0x43000000
	v_lshlrev_b32_e32 v17, 16, v9
	v_cvt_pk_u8_f32 v16, v16, 0, 0
	v_fmaak_f32 v8, v7, v8, 0x43000000
	v_and_b32_e32 v9, 0xffff0000, v9
	v_cvt_pk_u8_f32 v8, v8, 1, v16
	v_fmaak_f32 v16, v7, v17, 0x43000000
	v_cvt_pk_u8_f32 v8, v16, 2, v8
	v_fmaak_f32 v9, v7, v9, 0x43000000
	v_cvt_pk_u8_f32 v8, v9, 3, v8
	v_lshlrev_b32_e32 v9, 16, v10
	v_and_b32_e32 v10, 0xffff0000, v10
	v_fmaak_f32 v9, v7, v9, 0x43000000
	v_lshlrev_b32_e32 v16, 16, v11
	v_cvt_pk_u8_f32 v9, v9, 0, 0
	v_fmaak_f32 v10, v7, v10, 0x43000000
	v_and_b32_e32 v11, 0xffff0000, v11
	v_cvt_pk_u8_f32 v9, v10, 1, v9
	v_fmaak_f32 v10, v7, v16, 0x43000000
	v_cvt_pk_u8_f32 v9, v10, 2, v9
	v_fmaak_f32 v10, v7, v11, 0x43000000
	v_cvt_pk_u8_f32 v9, v10, 3, v9
	v_lshlrev_b32_e32 v10, 16, v12
	v_and_b32_e32 v11, 0xffff0000, v12
	v_fmaak_f32 v10, v7, v10, 0x43000000
	v_lshlrev_b32_e32 v12, 16, v13
	v_cvt_pk_u8_f32 v10, v10, 0, 0
	v_fmaak_f32 v11, v7, v11, 0x43000000
	v_and_b32_e32 v13, 0xffff0000, v13
	v_cvt_pk_u8_f32 v10, v11, 1, v10
	v_fmaak_f32 v11, v7, v12, 0x43000000
	v_cvt_pk_u8_f32 v10, v11, 2, v10
	v_fmaak_f32 v11, v7, v13, 0x43000000
	v_cvt_pk_u8_f32 v10, v11, 3, v10
	v_lshlrev_b32_e32 v11, 16, v14
	v_and_b32_e32 v12, 0xffff0000, v14
	v_fmaak_f32 v11, v7, v11, 0x43000000
	v_lshlrev_b32_e32 v13, 16, v15
	v_cvt_pk_u8_f32 v11, v11, 0, 0
	v_fmaak_f32 v12, v7, v12, 0x43000000
	v_and_b32_e32 v14, 0xffff0000, v15
	v_cvt_pk_u8_f32 v11, v12, 1, v11
	v_fmaak_f32 v12, v7, v13, 0x43000000
	v_xor_b32_e32 v8, 0x80808080, v8
	v_xor_b32_e32 v9, 0x80808080, v9
	v_cvt_pk_u8_f32 v11, v12, 2, v11
	v_fmaak_f32 v7, v7, v14, 0x43000000
	v_lshl_add_u64 v[12:13], s[4:5], 0, v[4:5]
	v_cvt_pk_u8_f32 v7, v7, 3, v11
	global_store_dwordx2 v[12:13], v[8:9], off
	v_lshl_add_u64 v[8:9], s[4:5], 0, v[2:3]
	v_xor_b32_e32 v10, 0x80808080, v10
	v_xor_b32_e32 v11, 0x80808080, v7
	global_store_dwordx2 v[8:9], v[10:11], off
	s_add_i32 s0, s0, 8
	s_ashr_i32 s4, s0, 4
	s_mul_hi_i32 s5, s4, 0x2e8ba2e9
	s_lshr_b32 s7, s5, 31
	s_ashr_i32 s5, s5, 1
	s_add_i32 s7, s5, s7
	s_mul_i32 s5, s7, 11
	s_sub_i32 s4, s4, s5
	s_mul_i32 s5, s66, 11
	s_add_i32 s8, s4, s5
	s_lshl_b32 s11, s8, 1
	s_add_i32 s10, s7, s13
	s_or_b32 s11, s11, s3
	s_and_b32 s6, s0, 15
	s_bfe_u32 s9, s0, 0x30001
	s_waitcnt vmcnt(6)
; #define GAS __attribute__((address_space(1)))
; __device__ __forceinline__ float bf_lo(unsigned w) { return __uint_as_float(w << 16); }
; __device__ __forceinline__ float bf_hi(unsigned w) { return __uint_as_float(w & 0xffff0000u); }
; __device__ __forceinline__ void phase_hidconv(LAS unsigned char* lds, const bf16_t* HIDb, unsigned char* HID8, const float* hmx, float* hrs, int grp, int rank, int wv) {
;     ...
;     for (int ui = wave; ui < 2 * 11 * 16; ui += 8) {
;         const int st8 = ui & 15, kk = (ui >> 4) % 11, h = (ui >> 4) / 11;
;         const int kt8 = mem * 11 + kk, rb = st8 >> 1, h2 = st8 & 1;
;         const GAS char* src = (const GAS char*)HIDb + ((size_t)(2 * pm + h) * KT_F + (2 * kt8 + h2)) * pg8::HTB + (size_t)(rb * 2048) + lane * 16;
;         GAS char* dst = (GAS char*)HID8 + ((size_t)(2 * pm + h) * KT_F8 + kt8) * pg8::HTB + (size_t)(st8 * 1024);
;         const u32x4 a = *(const GAS u32x4*)src, b = *(const GAS u32x4*)(src + 1024);
;         const float s_ = sc[h * 128 + rb * 16 + rr];
;         u32x2 wa, wb;
;         wa.x = cvt_i8x4(bf_lo(a.x) * s_, bf_hi(a.x) * s_, bf_lo(a.y) * s_, bf_hi(a.y) * s_); wa.y = cvt_i8x4(bf_lo(a.z) * s_, bf_hi(a.z) * s_, bf_lo(a.w) * s_, bf_hi(a.w) * s_);
;         wb.x = cvt_i8x4(bf_lo(b.x) * s_, bf_hi(b.x) * s_, bf_lo(b.y) * s_, bf_hi(b.y) * s_); wb.y = cvt_i8x4(bf_lo(b.z) * s_, bf_hi(b.z) * s_, bf_lo(b.w) * s_, bf_hi(b.w) * s_);
;         *(GAS u32x2*)(dst + d0) = wa; *(GAS u32x2*)(dst + d1) = wb;
	v_mov_b32_e32 v8, v72
	v_mov_b32_e32 v9, v73
	v_mov_b32_e32 v10, v74
	v_mov_b32_e32 v11, v75
	v_mov_b32_e32 v12, v76
	v_mov_b32_e32 v13, v77
	v_mov_b32_e32 v14, v78
	v_mov_b32_e32 v15, v79
	s_mul_hi_i32 s5, s10, 44
	s_mul_i32 s10, s10, 44
	s_ashr_i32 s11, s8, 31
	s_add_u32 s4, s10, s8
	s_addc_u32 s5, s5, s11
	s_lshl_b64 s[4:5], s[4:5], 14
	s_add_u32 s4, s1, s4
	s_addc_u32 s5, s2, s5
	s_lshl_b32 s6, s6, 10
	s_add_u32 s4, s4, s6
	s_addc_u32 s5, s5, 0
	s_lshl_b32 s6, s7, 9
	s_add_i32 s6, s40, s6
	s_lshl_b32 s7, s9, 6
	s_add_i32 s6, s6, s7
	v_lshl_add_u32 v7, v6, 2, s6
	ds_read_b32 v7, v7
	v_lshlrev_b32_e32 v16, 16, v8
	v_and_b32_e32 v8, 0xffff0000, v8
	s_waitcnt lgkmcnt(0)
	v_fmaak_f32 v16, v7, v16, 0x43000000
	v_lshlrev_b32_e32 v17, 16, v9
	v_cvt_pk_u8_f32 v16, v16, 0, 0
	v_fmaak_f32 v8, v7, v8, 0x43000000
	v_and_b32_e32 v9, 0xffff0000, v9
	v_cvt_pk_u8_f32 v8, v8, 1, v16
	v_fmaak_f32 v16, v7, v17, 0x43000000
	v_cvt_pk_u8_f32 v8, v16, 2, v8
	v_fmaak_f32 v9, v7, v9, 0x43000000
	v_cvt_pk_u8_f32 v8, v9, 3, v8
	v_lshlrev_b32_e32 v9, 16, v10
	v_and_b32_e32 v10, 0xffff0000, v10
	v_fmaak_f32 v9, v7, v9, 0x43000000
	v_lshlrev_b32_e32 v16, 16, v11
	v_cvt_pk_u8_f32 v9, v9, 0, 0
	v_fmaak_f32 v10, v7, v10, 0x43000000
	v_and_b32_e32 v11, 0xffff0000, v11
	v_cvt_pk_u8_f32 v9, v10, 1, v9
	v_fmaak_f32 v10, v7, v16, 0x43000000
	v_cvt_pk_u8_f32 v9, v10, 2, v9
	v_fmaak_f32 v10, v7, v11, 0x43000000
	v_cvt_pk_u8_f32 v9, v10, 3, v9
	v_lshlrev_b32_e32 v10, 16, v12
	v_and_b32_e32 v11, 0xffff0000, v12
	v_fmaak_f32 v10, v7, v10, 0x43000000
	v_lshlrev_b32_e32 v12, 16, v13
	v_cvt_pk_u8_f32 v10, v10, 0, 0
	v_fmaak_f32 v11, v7, v11, 0x43000000
	v_and_b32_e32 v13, 0xffff0000, v13
	v_cvt_pk_u8_f32 v10, v11, 1, v10
	v_fmaak_f32 v11, v7, v12, 0x43000000
	v_cvt_pk_u8_f32 v10, v11, 2, v10
	v_fmaak_f32 v11, v7, v13, 0x43000000
	v_cvt_pk_u8_f32 v10, v11, 3, v10
	v_lshlrev_b32_e32 v11, 16, v14
	v_and_b32_e32 v12, 0xffff0000, v14
	v_fmaak_f32 v11, v7, v11, 0x43000000
	v_lshlrev_b32_e32 v13, 16, v15
	v_cvt_pk_u8_f32 v11, v11, 0, 0
	v_fmaak_f32 v12, v7, v12, 0x43000000
	v_and_b32_e32 v14, 0xffff0000, v15
	v_cvt_pk_u8_f32 v11, v12, 1, v11
	v_fmaak_f32 v12, v7, v13, 0x43000000
	v_xor_b32_e32 v8, 0x80808080, v8
	v_xor_b32_e32 v9, 0x80808080, v9
	v_cvt_pk_u8_f32 v11, v12, 2, v11
	v_fmaak_f32 v7, v7, v14, 0x43000000
	v_lshl_add_u64 v[12:13], s[4:5], 0, v[4:5]
	v_cvt_pk_u8_f32 v7, v7, 3, v11
	global_store_dwordx2 v[12:13], v[8:9], off
	v_lshl_add_u64 v[8:9], s[4:5], 0, v[2:3]
	v_xor_b32_e32 v10, 0x80808080, v10
	v_xor_b32_e32 v11, 0x80808080, v7
	global_store_dwordx2 v[8:9], v[10:11], off
	s_add_i32 s0, s0, 8
	s_ashr_i32 s4, s0, 4
	s_mul_hi_i32 s5, s4, 0x2e8ba2e9
	s_lshr_b32 s7, s5, 31
	s_ashr_i32 s5, s5, 1
	s_add_i32 s7, s5, s7
	s_mul_i32 s5, s7, 11
	s_sub_i32 s4, s4, s5
	s_mul_i32 s5, s66, 11
	s_add_i32 s8, s4, s5
	s_lshl_b32 s11, s8, 1
	s_add_i32 s10, s7, s13
	s_or_b32 s11, s11, s3
	s_and_b32 s6, s0, 15
	s_bfe_u32 s9, s0, 0x30001
	s_waitcnt vmcnt(6)
	v_mov_b32_e32 v8, v80
	v_mov_b32_e32 v9, v81
	v_mov_b32_e32 v10, v82
	v_mov_b32_e32 v11, v83
	v_mov_b32_e32 v12, v84
	v_mov_b32_e32 v13, v85
	v_mov_b32_e32 v14, v86
	v_mov_b32_e32 v15, v87
	s_mul_hi_i32 s5, s10, 44
	s_mul_i32 s10, s10, 44
	s_ashr_i32 s11, s8, 31
	s_add_u32 s4, s10, s8
	s_addc_u32 s5, s5, s11
	s_lshl_b64 s[4:5], s[4:5], 14
	s_add_u32 s4, s1, s4
	s_addc_u32 s5, s2, s5
	s_lshl_b32 s6, s6, 10
	s_add_u32 s4, s4, s6
	s_addc_u32 s5, s5, 0
	s_lshl_b32 s6, s7, 9
	s_add_i32 s6, s40, s6
	s_lshl_b32 s7, s9, 6
	s_add_i32 s6, s6, s7
	v_lshl_add_u32 v7, v6, 2, s6
	ds_read_b32 v7, v7
	v_lshlrev_b32_e32 v16, 16, v8
	v_and_b32_e32 v8, 0xffff0000, v8
	s_waitcnt lgkmcnt(0)
; #define GAS __attribute__((address_space(1)))
; __device__ __forceinline__ float bf_lo(unsigned w) { return __uint_as_float(w << 16); }
; __device__ __forceinline__ float bf_hi(unsigned w) { return __uint_as_float(w & 0xffff0000u); }
; __device__ __forceinline__ void phase_hidconv(LAS unsigned char* lds, const bf16_t* HIDb, unsigned char* HID8, const float* hmx, float* hrs, int grp, int rank, int wv) {
;     ...
;     for (int ui = wave; ui < 2 * 11 * 16; ui += 8) {
;         const int st8 = ui & 15, kk = (ui >> 4) % 11, h = (ui >> 4) / 11;
;         const int kt8 = mem * 11 + kk, rb = st8 >> 1, h2 = st8 & 1;
;         const GAS char* src = (const GAS char*)HIDb + ((size_t)(2 * pm + h) * KT_F + (2 * kt8 + h2)) * pg8::HTB + (size_t)(rb * 2048) + lane * 16;
;         GAS char* dst = (GAS char*)HID8 + ((size_t)(2 * pm + h) * KT_F8 + kt8) * pg8::HTB + (size_t)(st8 * 1024);
;         const u32x4 a = *(const GAS u32x4*)src, b = *(const GAS u32x4*)(src + 1024);
;         const float s_ = sc[h * 128 + rb * 16 + rr];
;         u32x2 wa, wb;
;         wa.x = cvt_i8x4(bf_lo(a.x) * s_, bf_hi(a.x) * s_, bf_lo(a.y) * s_, bf_hi(a.y) * s_); wa.y = cvt_i8x4(bf_lo(a.z) * s_, bf_hi(a.z) * s_, bf_lo(a.w) * s_, bf_hi(a.w) * s_);
;         wb.x = cvt_i8x4(bf_lo(b.x) * s_, bf_hi(b.x) * s_, bf_lo(b.y) * s_, bf_hi(b.y) * s_); wb.y = cvt_i8x4(bf_lo(b.z) * s_, bf_hi(b.z) * s_, bf_lo(b.w) * s_, bf_hi(b.w) * s_);
;         *(GAS u32x2*)(dst + d0) = wa; *(GAS u32x2*)(dst + d1) = wb;
	v_fmaak_f32 v16, v7, v16, 0x43000000
	v_lshlrev_b32_e32 v17, 16, v9
	v_cvt_pk_u8_f32 v16, v16, 0, 0
	v_fmaak_f32 v8, v7, v8, 0x43000000
	v_and_b32_e32 v9, 0xffff0000, v9
	v_cvt_pk_u8_f32 v8, v8, 1, v16
	v_fmaak_f32 v16, v7, v17, 0x43000000
	v_cvt_pk_u8_f32 v8, v16, 2, v8
	v_fmaak_f32 v9, v7, v9, 0x43000000
	v_cvt_pk_u8_f32 v8, v9, 3, v8
	v_lshlrev_b32_e32 v9, 16, v10
	v_and_b32_e32 v10, 0xffff0000, v10
	v_fmaak_f32 v9, v7, v9, 0x43000000
	v_lshlrev_b32_e32 v16, 16, v11
	v_cvt_pk_u8_f32 v9, v9, 0, 0
	v_fmaak_f32 v10, v7, v10, 0x43000000
	v_and_b32_e32 v11, 0xffff0000, v11
	v_cvt_pk_u8_f32 v9, v10, 1, v9
	v_fmaak_f32 v10, v7, v16, 0x43000000
	v_cvt_pk_u8_f32 v9, v10, 2, v9
	v_fmaak_f32 v10, v7, v11, 0x43000000
	v_cvt_pk_u8_f32 v9, v10, 3, v9
	v_lshlrev_b32_e32 v10, 16, v12
	v_and_b32_e32 v11, 0xffff0000, v12
	v_fmaak_f32 v10, v7, v10, 0x43000000
	v_lshlrev_b32_e32 v12, 16, v13
	v_cvt_pk_u8_f32 v10, v10, 0, 0
	v_fmaak_f32 v11, v7, v11, 0x43000000
	v_and_b32_e32 v13, 0xffff0000, v13
	v_cvt_pk_u8_f32 v10, v11, 1, v10
	v_fmaak_f32 v11, v7, v12, 0x43000000
	v_cvt_pk_u8_f32 v10, v11, 2, v10
	v_fmaak_f32 v11, v7, v13, 0x43000000
	v_cvt_pk_u8_f32 v10, v11, 3, v10
	v_lshlrev_b32_e32 v11, 16, v14
	v_and_b32_e32 v12, 0xffff0000, v14
	v_fmaak_f32 v11, v7, v11, 0x43000000
	v_lshlrev_b32_e32 v13, 16, v15
	v_cvt_pk_u8_f32 v11, v11, 0, 0
	v_fmaak_f32 v12, v7, v12, 0x43000000
	v_and_b32_e32 v14, 0xffff0000, v15
	v_cvt_pk_u8_f32 v11, v12, 1, v11
	v_fmaak_f32 v12, v7, v13, 0x43000000
	v_xor_b32_e32 v8, 0x80808080, v8
	v_xor_b32_e32 v9, 0x80808080, v9
	v_cvt_pk_u8_f32 v11, v12, 2, v11
	v_fmaak_f32 v7, v7, v14, 0x43000000
	v_lshl_add_u64 v[12:13], s[4:5], 0, v[4:5]
	v_cvt_pk_u8_f32 v7, v7, 3, v11
	global_store_dwordx2 v[12:13], v[8:9], off
	v_lshl_add_u64 v[8:9], s[4:5], 0, v[2:3]
	v_xor_b32_e32 v10, 0x80808080, v10
	v_xor_b32_e32 v11, 0x80808080, v7
	global_store_dwordx2 v[8:9], v[10:11], off
	s_add_i32 s0, s0, 8
	s_ashr_i32 s4, s0, 4
	s_mul_hi_i32 s5, s4, 0x2e8ba2e9
	s_lshr_b32 s7, s5, 31
	s_ashr_i32 s5, s5, 1
	s_add_i32 s7, s5, s7
	s_mul_i32 s5, s7, 11
	s_sub_i32 s4, s4, s5
	s_mul_i32 s5, s66, 11
	s_add_i32 s8, s4, s5
	s_lshl_b32 s11, s8, 1
	s_add_i32 s10, s7, s13
	s_or_b32 s11, s11, s3
	s_and_b32 s6, s0, 15
	s_bfe_u32 s9, s0, 0x30001
	s_waitcnt vmcnt(6)
	v_mov_b32_e32 v8, v88
	v_mov_b32_e32 v9, v89
	v_mov_b32_e32 v10, v90
	v_mov_b32_e32 v11, v91
	v_mov_b32_e32 v12, v92
	v_mov_b32_e32 v13, v93
	v_mov_b32_e32 v14, v94
	v_mov_b32_e32 v15, v95
	s_mul_hi_i32 s5, s10, 44
	s_mul_i32 s10, s10, 44
	s_ashr_i32 s11, s8, 31
	s_add_u32 s4, s10, s8
	s_addc_u32 s5, s5, s11
	s_lshl_b64 s[4:5], s[4:5], 14
	s_add_u32 s4, s1, s4
	s_addc_u32 s5, s2, s5
	s_lshl_b32 s6, s6, 10
	s_add_u32 s4, s4, s6
	s_addc_u32 s5, s5, 0
	s_lshl_b32 s6, s7, 9
	s_add_i32 s6, s40, s6
	s_lshl_b32 s7, s9, 6
	s_add_i32 s6, s6, s7
	v_lshl_add_u32 v7, v6, 2, s6
	ds_read_b32 v7, v7
	v_lshlrev_b32_e32 v16, 16, v8
	v_and_b32_e32 v8, 0xffff0000, v8
	s_waitcnt lgkmcnt(0)
	v_fmaak_f32 v16, v7, v16, 0x43000000
	v_lshlrev_b32_e32 v17, 16, v9
	v_cvt_pk_u8_f32 v16, v16, 0, 0
	v_fmaak_f32 v8, v7, v8, 0x43000000
	v_and_b32_e32 v9, 0xffff0000, v9
	v_cvt_pk_u8_f32 v8, v8, 1, v16
	v_fmaak_f32 v16, v7, v17, 0x43000000
	v_cvt_pk_u8_f32 v8, v16, 2, v8
	v_fmaak_f32 v9, v7, v9, 0x43000000
	v_cvt_pk_u8_f32 v8, v9, 3, v8
	v_lshlrev_b32_e32 v9, 16, v10
	v_and_b32_e32 v10, 0xffff0000, v10
	v_fmaak_f32 v9, v7, v9, 0x43000000
	v_lshlrev_b32_e32 v16, 16, v11
	v_cvt_pk_u8_f32 v9, v9, 0, 0
	v_fmaak_f32 v10, v7, v10, 0x43000000
	v_and_b32_e32 v11, 0xffff0000, v11
	v_cvt_pk_u8_f32 v9, v10, 1, v9
	v_fmaak_f32 v10, v7, v16, 0x43000000
	v_cvt_pk_u8_f32 v9, v10, 2, v9
	v_fmaak_f32 v10, v7, v11, 0x43000000
	v_cvt_pk_u8_f32 v9, v10, 3, v9
	v_lshlrev_b32_e32 v10, 16, v12
	v_and_b32_e32 v11, 0xffff0000, v12
	v_fmaak_f32 v10, v7, v10, 0x43000000
	v_lshlrev_b32_e32 v12, 16, v13
	v_cvt_pk_u8_f32 v10, v10, 0, 0
	v_fmaak_f32 v11, v7, v11, 0x43000000
	v_and_b32_e32 v13, 0xffff0000, v13
	v_cvt_pk_u8_f32 v10, v11, 1, v10
	v_fmaak_f32 v11, v7, v12, 0x43000000
	v_cvt_pk_u8_f32 v10, v11, 2, v10
	v_fmaak_f32 v11, v7, v13, 0x43000000
	v_cvt_pk_u8_f32 v10, v11, 3, v10
	v_lshlrev_b32_e32 v11, 16, v14
	v_and_b32_e32 v12, 0xffff0000, v14
	v_fmaak_f32 v11, v7, v11, 0x43000000
	v_lshlrev_b32_e32 v13, 16, v15
	v_cvt_pk_u8_f32 v11, v11, 0, 0
	v_fmaak_f32 v12, v7, v12, 0x43000000
	v_and_b32_e32 v14, 0xffff0000, v15
	v_cvt_pk_u8_f32 v11, v12, 1, v11
	v_fmaak_f32 v12, v7, v13, 0x43000000
	v_xor_b32_e32 v8, 0x80808080, v8
	v_xor_b32_e32 v9, 0x80808080, v9
	v_cvt_pk_u8_f32 v11, v12, 2, v11
	v_fmaak_f32 v7, v7, v14, 0x43000000
	v_lshl_add_u64 v[12:13], s[4:5], 0, v[4:5]
	v_cvt_pk_u8_f32 v7, v7, 3, v11
	global_store_dwordx2 v[12:13], v[8:9], off
	v_lshl_add_u64 v[8:9], s[4:5], 0, v[2:3]
	v_xor_b32_e32 v10, 0x80808080, v10
	v_xor_b32_e32 v11, 0x80808080, v7
	global_store_dwordx2 v[8:9], v[10:11], off
	s_add_i32 s0, s0, 8
	s_cmpk_lt_i32 s0, 0x160
	s_cbranch_scc1 .LBB0_573
